# v40
# baseline (speedup 1.0000x reference)
.LBB0_431:
	s_lshl_b32 s2, s20, 2
	s_add_i32 s68, s34, s2
	v_lshl_add_u64 v[50:51], s[68:69], 0, v[0:1]
	s_waitcnt vmcnt(0)
	s_waitcnt vmcnt(0)
	ds_read_b128 v[166:169], v50
	ds_read_b128 v[162:165], v50 offset:64
	ds_read_b128 v[158:161], v50 offset:128
	ds_read_b128 v[138:141], v50 offset:192
	ds_read_b128 v[118:121], v50 offset:256
	ds_read_b128 v[98:101], v50 offset:320
	ds_read_b128 v[78:81], v50 offset:384
	ds_read_b128 v[58:61], v50 offset:448
	s_load_dword s2, s[78:79], 0x0
	v_mov_b32_e32 v50, 0
	v_mov_b32_e32 v51, 0
	v_mov_b32_e32 v52, 0
	v_mov_b32_e32 v53, 0
	s_waitcnt lgkmcnt(0)
	s_add_i32 s31, s2, s31
	s_cmpk_lt_i32 s31, 0x580
	s_cselect_b64 s[10:11], -1, 0
	s_and_b64 vcc, exec, s[10:11]
	v_mov_b32_e32 v54, 0
	v_mov_b32_e32 v55, 0
	v_mov_b32_e32 v56, 0
	v_mov_b32_e32 v57, 0
	s_cbranch_vccz .LBB0_433
	s_ashr_i32 s2, s31, 31
	s_lshr_b32 s2, s2, 29
	s_add_i32 s2, s31, s2
	s_ashr_i32 s8, s2, 3
	s_and_b32 s2, s2, -8
	s_sub_i32 s2, s31, s2
	s_cmp_lt_i32 s2, 0
	s_cselect_b32 s9, s73, 0xb0
	s_mul_i32 s2, s9, s2
	s_add_i32 s2, s2, s8
	s_mul_hi_i32 s8, s2, 0x2e8ba2e9
	s_lshr_b32 s9, s8, 31
	s_ashr_i32 s8, s8, 4
	s_add_i32 s8, s8, s9
	s_mul_i32 s9, s8, 0x58
	s_sub_i32 s2, s2, s9
	s_bfe_i32 s9, s2, 0x80000
	s_bfe_u32 s9, s9, 0x2000d
	s_add_i32 s9, s2, s9
	s_bfe_i32 s13, s9, 0x80000
	s_and_b32 s9, s9, 0xfc
	s_sub_i32 s2, s2, s9
	s_sext_i32_i8 s2, s2
	s_lshl_b32 s8, s8, 10
	s_lshl_b32 s2, s2, 8
	s_sext_i32_i16 s13, s13
	s_add_i32 s8, s2, s8
	s_lshl_b32 s2, s13, 6
	s_ashr_i32 s9, s8, 31
	s_and_b32 s34, s2, 0xffffff00
	v_add_u32_e32 v50, s8, v203
	s_lshl_b64 s[8:9], s[8:9], 11
	s_add_u32 s64, s94, s8
	s_addc_u32 s2, s95, s9
	s_ashr_i32 s35, s34, 31
	v_ashrrev_i32_e32 v51, 31, v50
	s_lshl_b64 s[8:9], s[34:35], 11
	v_lshlrev_b64 v[50:51], 6, v[50:51]
	s_add_u32 s36, s18, s8
	v_lshl_add_u64 v[54:55], v[172:173], 0, v[50:51]
	s_addc_u32 s8, s19, s9
	s_and_b32 s65, s2, 0xffff
	global_load_dwordx4 v[50:53], v[54:55], off
	s_nop 0
	global_load_dwordx4 v[54:57], v[54:55], off offset:16
	s_and_b32 s37, s8, 0xffff
	s_mov_b32 s38, s66
	s_mov_b32 s39, s67
.LBB0_433:
	v_add_u32_e32 v177, s12, v205
	s_or_b32 s2, s14, s21
	s_ashr_i32 s2, s2, 1
	v_or_b32_e32 v176, s2, v202
	v_mov_b64_e32 v[174:175], s[76:77]
	s_movk_i32 s8, 0x1580
	v_mad_i64_i32 v[174:175], s[8:9], v177, s8, v[174:175]
	v_ashrrev_i32_e32 v177, 31, v176
	v_lshl_add_u64 v[174:175], v[176:177], 1, v[174:175]
	s_cmpk_lt_i32 s2, 0xaa1
	s_cbranch_scc1 .Lsw_epi_full
	s_and_b64 vcc, exec, s[10:11]
	s_cbranch_vccz .Lsw_epi_done
	s_mov_b32 m0, s22
	s_nop 0
	buffer_load_dwordx4 v201, s[64:67], 0 offen lds
	s_mov_b32 m0, s23
	s_nop 0
	buffer_load_dwordx4 v248, s[36:39], 0 offen lds
	s_mov_b32 m0, s24
	s_nop 0
	buffer_load_dwordx4 v201, s[64:67], s67 offen lds
	s_mov_b32 m0, s25
	s_nop 0
	buffer_load_dwordx4 v248, s[36:39], s67 offen lds
	s_mov_b32 m0, s26
	s_nop 0
	buffer_load_dwordx4 v201, s[64:67], s83 offen lds
	s_mov_b32 m0, s27
	s_nop 0
	buffer_load_dwordx4 v248, s[36:39], s83 offen lds
	s_mov_b32 m0, s28
	s_nop 0
	buffer_load_dwordx4 v201, s[64:67], s90 offen lds
	s_mov_b32 m0, s29
	s_nop 0
	buffer_load_dwordx4 v248, s[36:39], s90 offen lds
	s_branch .Lsw_epi_done
.Lsw_epi_full:
	v_lshlrev_b32_e32 v236, 1, v202
	v_mov_b32_e32 v237, 0
	v_lshl_add_u64 v[174:175], v[174:175], 0, v[236:237]
	v_mul_f32_e32 v228, v150, v166
	v_mul_f32_e32 v229, v142, v166
	v_mul_f32_e32 v230, 0xbfb8aa3b, v228
	v_mul_f32_e32 v231, 0xbfb8aa3b, v229
	v_exp_f32_e32 v230, v230
	v_exp_f32_e32 v231, v231
	v_mul_f32_e32 v232, v154, v166
	v_mul_f32_e32 v233, v146, v166
	v_add_f32_e32 v230, 1.0, v230
	v_add_f32_e32 v231, 1.0, v231
	v_rcp_f32_e32 v230, v230
	v_rcp_f32_e32 v231, v231
	v_mul_f32_e32 v228, v228, v230
	v_mul_f32_e32 v229, v229, v231
	v_mul_f32_e32 v232, v232, v228
	v_mul_f32_e32 v233, v233, v229
	v_cvt_pk_bf16_f32 v234, v232, v233
	global_store_dword v[174:175], v234, off
	v_lshl_add_u64 v[174:175], v[174:175], 0, s[98:99]
	s_and_b64 vcc, exec, s[10:11]
	s_cbranch_vccz .Lsw_pf_skip0
	s_mov_b32 m0, s22
	s_nop 0
	buffer_load_dwordx4 v201, s[64:67], 0 offen lds
.Lsw_pf_skip0:
	v_mul_f32_e32 v228, v151, v167
	v_mul_f32_e32 v229, v143, v167
	v_mul_f32_e32 v230, 0xbfb8aa3b, v228
	v_mul_f32_e32 v231, 0xbfb8aa3b, v229
	v_exp_f32_e32 v230, v230
	v_exp_f32_e32 v231, v231
	v_mul_f32_e32 v232, v155, v167
	v_mul_f32_e32 v233, v147, v167
	v_add_f32_e32 v230, 1.0, v230
	v_add_f32_e32 v231, 1.0, v231
	v_rcp_f32_e32 v230, v230
	v_rcp_f32_e32 v231, v231
	v_mul_f32_e32 v228, v228, v230
	v_mul_f32_e32 v229, v229, v231
	v_mul_f32_e32 v232, v232, v228
	v_mul_f32_e32 v233, v233, v229
	v_cvt_pk_bf16_f32 v235, v232, v233
	global_store_dword v[174:175], v235, off
	v_lshl_add_u64 v[174:175], v[174:175], 0, s[98:99]
	v_mul_f32_e32 v228, v152, v168
	v_mul_f32_e32 v229, v144, v168
	v_mul_f32_e32 v230, 0xbfb8aa3b, v228
	v_mul_f32_e32 v231, 0xbfb8aa3b, v229
	v_exp_f32_e32 v230, v230
	v_exp_f32_e32 v231, v231
	v_mul_f32_e32 v232, v156, v168
	v_mul_f32_e32 v233, v148, v168
	v_add_f32_e32 v230, 1.0, v230
	v_add_f32_e32 v231, 1.0, v231
	v_rcp_f32_e32 v230, v230
	v_rcp_f32_e32 v231, v231
	v_mul_f32_e32 v228, v228, v230
	v_mul_f32_e32 v229, v229, v231
	v_mul_f32_e32 v232, v232, v228
	v_mul_f32_e32 v233, v233, v229
	v_cvt_pk_bf16_f32 v234, v232, v233
	global_store_dword v[174:175], v234, off
	v_lshl_add_u64 v[174:175], v[174:175], 0, s[98:99]
	v_mul_f32_e32 v228, v153, v169
	v_mul_f32_e32 v229, v145, v169
	v_mul_f32_e32 v230, 0xbfb8aa3b, v228
	v_mul_f32_e32 v231, 0xbfb8aa3b, v229
	v_exp_f32_e32 v230, v230
	v_exp_f32_e32 v231, v231
	v_mul_f32_e32 v232, v157, v169
	v_mul_f32_e32 v233, v149, v169
	v_add_f32_e32 v230, 1.0, v230
	v_add_f32_e32 v231, 1.0, v231
	v_rcp_f32_e32 v230, v230
	v_rcp_f32_e32 v231, v231
	v_mul_f32_e32 v228, v228, v230
	v_mul_f32_e32 v229, v229, v231
	v_mul_f32_e32 v232, v232, v228
	v_mul_f32_e32 v233, v233, v229
	v_cvt_pk_bf16_f32 v235, v232, v233
	global_store_dword v[174:175], v235, off
	v_lshl_add_u64 v[174:175], v[174:175], 0, s[98:99]
	v_lshl_add_u64 v[174:175], v[174:175], 0, s[44:45]
	v_mul_f32_e32 v228, v130, v162
	v_mul_f32_e32 v229, v122, v162
	v_mul_f32_e32 v230, 0xbfb8aa3b, v228
	v_mul_f32_e32 v231, 0xbfb8aa3b, v229
	v_exp_f32_e32 v230, v230
	v_exp_f32_e32 v231, v231
	v_mul_f32_e32 v232, v134, v162
	v_mul_f32_e32 v233, v126, v162
	v_add_f32_e32 v230, 1.0, v230
	v_add_f32_e32 v231, 1.0, v231
	v_rcp_f32_e32 v230, v230
	v_rcp_f32_e32 v231, v231
	v_mul_f32_e32 v228, v228, v230
	v_mul_f32_e32 v229, v229, v231
	v_mul_f32_e32 v232, v232, v228
	v_mul_f32_e32 v233, v233, v229
	v_cvt_pk_bf16_f32 v234, v232, v233
	global_store_dword v[174:175], v234, off
	v_lshl_add_u64 v[174:175], v[174:175], 0, s[98:99]
	s_and_b64 vcc, exec, s[10:11]
	s_cbranch_vccz .Lsw_pf_skip1
	s_mov_b32 m0, s23
	s_nop 0
	buffer_load_dwordx4 v248, s[36:39], 0 offen lds
.Lsw_pf_skip1:
	v_mul_f32_e32 v228, v131, v163
	v_mul_f32_e32 v229, v123, v163
	v_mul_f32_e32 v230, 0xbfb8aa3b, v228
	v_mul_f32_e32 v231, 0xbfb8aa3b, v229
	v_exp_f32_e32 v230, v230
	v_exp_f32_e32 v231, v231
	v_mul_f32_e32 v232, v135, v163
	v_mul_f32_e32 v233, v127, v163
	v_add_f32_e32 v230, 1.0, v230
	v_add_f32_e32 v231, 1.0, v231
	v_rcp_f32_e32 v230, v230
	v_rcp_f32_e32 v231, v231
	v_mul_f32_e32 v228, v228, v230
	v_mul_f32_e32 v229, v229, v231
	v_mul_f32_e32 v232, v232, v228
	v_mul_f32_e32 v233, v233, v229
	v_cvt_pk_bf16_f32 v235, v232, v233
	global_store_dword v[174:175], v235, off
	v_lshl_add_u64 v[174:175], v[174:175], 0, s[98:99]
	v_mul_f32_e32 v228, v132, v164
	v_mul_f32_e32 v229, v124, v164
	v_mul_f32_e32 v230, 0xbfb8aa3b, v228
	v_mul_f32_e32 v231, 0xbfb8aa3b, v229
	v_exp_f32_e32 v230, v230
	v_exp_f32_e32 v231, v231
	v_mul_f32_e32 v232, v136, v164
	v_mul_f32_e32 v233, v128, v164
	v_add_f32_e32 v230, 1.0, v230
	v_add_f32_e32 v231, 1.0, v231
	v_rcp_f32_e32 v230, v230
	v_rcp_f32_e32 v231, v231
	v_mul_f32_e32 v228, v228, v230
	v_mul_f32_e32 v229, v229, v231
	v_mul_f32_e32 v232, v232, v228
	v_mul_f32_e32 v233, v233, v229
	v_cvt_pk_bf16_f32 v234, v232, v233
	global_store_dword v[174:175], v234, off
	v_lshl_add_u64 v[174:175], v[174:175], 0, s[98:99]
	v_mul_f32_e32 v228, v133, v165
	v_mul_f32_e32 v229, v125, v165
	v_mul_f32_e32 v230, 0xbfb8aa3b, v228
	v_mul_f32_e32 v231, 0xbfb8aa3b, v229
	v_exp_f32_e32 v230, v230
	v_exp_f32_e32 v231, v231
	v_mul_f32_e32 v232, v137, v165
	v_mul_f32_e32 v233, v129, v165
	v_add_f32_e32 v230, 1.0, v230
	v_add_f32_e32 v231, 1.0, v231
	v_rcp_f32_e32 v230, v230
	v_rcp_f32_e32 v231, v231
	v_mul_f32_e32 v228, v228, v230
	v_mul_f32_e32 v229, v229, v231
	v_mul_f32_e32 v232, v232, v228
	v_mul_f32_e32 v233, v233, v229
	v_cvt_pk_bf16_f32 v235, v232, v233
	global_store_dword v[174:175], v235, off
	v_lshl_add_u64 v[174:175], v[174:175], 0, s[98:99]
	v_lshl_add_u64 v[174:175], v[174:175], 0, s[44:45]
	v_mul_f32_e32 v228, v110, v158
	v_mul_f32_e32 v229, v102, v158
	v_mul_f32_e32 v230, 0xbfb8aa3b, v228
	v_mul_f32_e32 v231, 0xbfb8aa3b, v229
	v_exp_f32_e32 v230, v230
	v_exp_f32_e32 v231, v231
	v_mul_f32_e32 v232, v114, v158
	v_mul_f32_e32 v233, v106, v158
	v_add_f32_e32 v230, 1.0, v230
	v_add_f32_e32 v231, 1.0, v231
	v_rcp_f32_e32 v230, v230
	v_rcp_f32_e32 v231, v231
	v_mul_f32_e32 v228, v228, v230
	v_mul_f32_e32 v229, v229, v231
	v_mul_f32_e32 v232, v232, v228
	v_mul_f32_e32 v233, v233, v229
	v_cvt_pk_bf16_f32 v234, v232, v233
	global_store_dword v[174:175], v234, off
	v_lshl_add_u64 v[174:175], v[174:175], 0, s[98:99]
	s_and_b64 vcc, exec, s[10:11]
	s_cbranch_vccz .Lsw_pf_skip2
	s_mov_b32 m0, s24
	s_nop 0
	buffer_load_dwordx4 v201, s[64:67], s67 offen lds
.Lsw_pf_skip2:
	v_mul_f32_e32 v228, v111, v159
	v_mul_f32_e32 v229, v103, v159
	v_mul_f32_e32 v230, 0xbfb8aa3b, v228
	v_mul_f32_e32 v231, 0xbfb8aa3b, v229
	v_exp_f32_e32 v230, v230
	v_exp_f32_e32 v231, v231
	v_mul_f32_e32 v232, v115, v159
	v_mul_f32_e32 v233, v107, v159
	v_add_f32_e32 v230, 1.0, v230
	v_add_f32_e32 v231, 1.0, v231
	v_rcp_f32_e32 v230, v230
	v_rcp_f32_e32 v231, v231
	v_mul_f32_e32 v228, v228, v230
	v_mul_f32_e32 v229, v229, v231
	v_mul_f32_e32 v232, v232, v228
	v_mul_f32_e32 v233, v233, v229
	v_cvt_pk_bf16_f32 v235, v232, v233
	global_store_dword v[174:175], v235, off
	v_lshl_add_u64 v[174:175], v[174:175], 0, s[98:99]
	v_mul_f32_e32 v228, v112, v160
	v_mul_f32_e32 v229, v104, v160
	v_mul_f32_e32 v230, 0xbfb8aa3b, v228
	v_mul_f32_e32 v231, 0xbfb8aa3b, v229
	v_exp_f32_e32 v230, v230
	v_exp_f32_e32 v231, v231
	v_mul_f32_e32 v232, v116, v160
	v_mul_f32_e32 v233, v108, v160
	v_add_f32_e32 v230, 1.0, v230
	v_add_f32_e32 v231, 1.0, v231
	v_rcp_f32_e32 v230, v230
	v_rcp_f32_e32 v231, v231
	v_mul_f32_e32 v228, v228, v230
	v_mul_f32_e32 v229, v229, v231
	v_mul_f32_e32 v232, v232, v228
	v_mul_f32_e32 v233, v233, v229
	v_cvt_pk_bf16_f32 v234, v232, v233
	global_store_dword v[174:175], v234, off
	v_lshl_add_u64 v[174:175], v[174:175], 0, s[98:99]
	v_mul_f32_e32 v228, v113, v161
	v_mul_f32_e32 v229, v105, v161
	v_mul_f32_e32 v230, 0xbfb8aa3b, v228
	v_mul_f32_e32 v231, 0xbfb8aa3b, v229
	v_exp_f32_e32 v230, v230
	v_exp_f32_e32 v231, v231
	v_mul_f32_e32 v232, v117, v161
	v_mul_f32_e32 v233, v109, v161
	v_add_f32_e32 v230, 1.0, v230
	v_add_f32_e32 v231, 1.0, v231
	v_rcp_f32_e32 v230, v230
	v_rcp_f32_e32 v231, v231
	v_mul_f32_e32 v228, v228, v230
	v_mul_f32_e32 v229, v229, v231
	v_mul_f32_e32 v232, v232, v228
	v_mul_f32_e32 v233, v233, v229
	v_cvt_pk_bf16_f32 v235, v232, v233
	global_store_dword v[174:175], v235, off
	v_lshl_add_u64 v[174:175], v[174:175], 0, s[98:99]
	v_lshl_add_u64 v[174:175], v[174:175], 0, s[44:45]
	v_mul_f32_e32 v228, v90, v138
	v_mul_f32_e32 v229, v82, v138
	v_mul_f32_e32 v230, 0xbfb8aa3b, v228
	v_mul_f32_e32 v231, 0xbfb8aa3b, v229
	v_exp_f32_e32 v230, v230
	v_exp_f32_e32 v231, v231
	v_mul_f32_e32 v232, v94, v138
	v_mul_f32_e32 v233, v86, v138
	v_add_f32_e32 v230, 1.0, v230
	v_add_f32_e32 v231, 1.0, v231
	v_rcp_f32_e32 v230, v230
	v_rcp_f32_e32 v231, v231
	v_mul_f32_e32 v228, v228, v230
	v_mul_f32_e32 v229, v229, v231
	v_mul_f32_e32 v232, v232, v228
	v_mul_f32_e32 v233, v233, v229
	v_cvt_pk_bf16_f32 v234, v232, v233
	global_store_dword v[174:175], v234, off
	v_lshl_add_u64 v[174:175], v[174:175], 0, s[98:99]
	s_and_b64 vcc, exec, s[10:11]
	s_cbranch_vccz .Lsw_pf_skip3
	s_mov_b32 m0, s25
	s_nop 0
	buffer_load_dwordx4 v248, s[36:39], s67 offen lds
.Lsw_pf_skip3:
	v_mul_f32_e32 v228, v91, v139
	v_mul_f32_e32 v229, v83, v139
	v_mul_f32_e32 v230, 0xbfb8aa3b, v228
	v_mul_f32_e32 v231, 0xbfb8aa3b, v229
	v_exp_f32_e32 v230, v230
	v_exp_f32_e32 v231, v231
	v_mul_f32_e32 v232, v95, v139
	v_mul_f32_e32 v233, v87, v139
	v_add_f32_e32 v230, 1.0, v230
	v_add_f32_e32 v231, 1.0, v231
	v_rcp_f32_e32 v230, v230
	v_rcp_f32_e32 v231, v231
	v_mul_f32_e32 v228, v228, v230
	v_mul_f32_e32 v229, v229, v231
	v_mul_f32_e32 v232, v232, v228
	v_mul_f32_e32 v233, v233, v229
	v_cvt_pk_bf16_f32 v235, v232, v233
	global_store_dword v[174:175], v235, off
	v_lshl_add_u64 v[174:175], v[174:175], 0, s[98:99]
	v_mul_f32_e32 v228, v92, v140
	v_mul_f32_e32 v229, v84, v140
	v_mul_f32_e32 v230, 0xbfb8aa3b, v228
	v_mul_f32_e32 v231, 0xbfb8aa3b, v229
	v_exp_f32_e32 v230, v230
	v_exp_f32_e32 v231, v231
	v_mul_f32_e32 v232, v96, v140
	v_mul_f32_e32 v233, v88, v140
	v_add_f32_e32 v230, 1.0, v230
	v_add_f32_e32 v231, 1.0, v231
	v_rcp_f32_e32 v230, v230
	v_rcp_f32_e32 v231, v231
	v_mul_f32_e32 v228, v228, v230
	v_mul_f32_e32 v229, v229, v231
	v_mul_f32_e32 v232, v232, v228
	v_mul_f32_e32 v233, v233, v229
	v_cvt_pk_bf16_f32 v234, v232, v233
	global_store_dword v[174:175], v234, off
	v_lshl_add_u64 v[174:175], v[174:175], 0, s[98:99]
	v_mul_f32_e32 v228, v93, v141
	v_mul_f32_e32 v229, v85, v141
	v_mul_f32_e32 v230, 0xbfb8aa3b, v228
	v_mul_f32_e32 v231, 0xbfb8aa3b, v229
	v_exp_f32_e32 v230, v230
	v_exp_f32_e32 v231, v231
	v_mul_f32_e32 v232, v97, v141
	v_mul_f32_e32 v233, v89, v141
	v_add_f32_e32 v230, 1.0, v230
	v_add_f32_e32 v231, 1.0, v231
	v_rcp_f32_e32 v230, v230
	v_rcp_f32_e32 v231, v231
	v_mul_f32_e32 v228, v228, v230
	v_mul_f32_e32 v229, v229, v231
	v_mul_f32_e32 v232, v232, v228
	v_mul_f32_e32 v233, v233, v229
	v_cvt_pk_bf16_f32 v235, v232, v233
	global_store_dword v[174:175], v235, off
	v_lshl_add_u64 v[174:175], v[174:175], 0, s[98:99]
	v_lshl_add_u64 v[174:175], v[174:175], 0, s[44:45]
	v_mul_f32_e32 v228, v70, v118
	v_mul_f32_e32 v229, v62, v118
	v_mul_f32_e32 v230, 0xbfb8aa3b, v228
	v_mul_f32_e32 v231, 0xbfb8aa3b, v229
	v_exp_f32_e32 v230, v230
	v_exp_f32_e32 v231, v231
	v_mul_f32_e32 v232, v74, v118
	v_mul_f32_e32 v233, v66, v118
	v_add_f32_e32 v230, 1.0, v230
	v_add_f32_e32 v231, 1.0, v231
	v_rcp_f32_e32 v230, v230
	v_rcp_f32_e32 v231, v231
	v_mul_f32_e32 v228, v228, v230
	v_mul_f32_e32 v229, v229, v231
	v_mul_f32_e32 v232, v232, v228
	v_mul_f32_e32 v233, v233, v229
	v_cvt_pk_bf16_f32 v234, v232, v233
	global_store_dword v[174:175], v234, off
	v_lshl_add_u64 v[174:175], v[174:175], 0, s[98:99]
	s_and_b64 vcc, exec, s[10:11]
	s_cbranch_vccz .Lsw_pf_skip4
	s_mov_b32 m0, s26
	s_nop 0
	buffer_load_dwordx4 v201, s[64:67], s83 offen lds
.Lsw_pf_skip4:
	v_mul_f32_e32 v228, v71, v119
	v_mul_f32_e32 v229, v63, v119
	v_mul_f32_e32 v230, 0xbfb8aa3b, v228
	v_mul_f32_e32 v231, 0xbfb8aa3b, v229
	v_exp_f32_e32 v230, v230
	v_exp_f32_e32 v231, v231
	v_mul_f32_e32 v232, v75, v119
	v_mul_f32_e32 v233, v67, v119
	v_add_f32_e32 v230, 1.0, v230
	v_add_f32_e32 v231, 1.0, v231
	v_rcp_f32_e32 v230, v230
	v_rcp_f32_e32 v231, v231
	v_mul_f32_e32 v228, v228, v230
	v_mul_f32_e32 v229, v229, v231
	v_mul_f32_e32 v232, v232, v228
	v_mul_f32_e32 v233, v233, v229
	v_cvt_pk_bf16_f32 v235, v232, v233
	global_store_dword v[174:175], v235, off
	v_lshl_add_u64 v[174:175], v[174:175], 0, s[98:99]
	v_mul_f32_e32 v228, v72, v120
	v_mul_f32_e32 v229, v64, v120
	v_mul_f32_e32 v230, 0xbfb8aa3b, v228
	v_mul_f32_e32 v231, 0xbfb8aa3b, v229
	v_exp_f32_e32 v230, v230
	v_exp_f32_e32 v231, v231
	v_mul_f32_e32 v232, v76, v120
	v_mul_f32_e32 v233, v68, v120
	v_add_f32_e32 v230, 1.0, v230
	v_add_f32_e32 v231, 1.0, v231
	v_rcp_f32_e32 v230, v230
	v_rcp_f32_e32 v231, v231
	v_mul_f32_e32 v228, v228, v230
	v_mul_f32_e32 v229, v229, v231
	v_mul_f32_e32 v232, v232, v228
	v_mul_f32_e32 v233, v233, v229
	v_cvt_pk_bf16_f32 v234, v232, v233
	global_store_dword v[174:175], v234, off
	v_lshl_add_u64 v[174:175], v[174:175], 0, s[98:99]
	v_mul_f32_e32 v228, v73, v121
	v_mul_f32_e32 v229, v65, v121
	v_mul_f32_e32 v230, 0xbfb8aa3b, v228
	v_mul_f32_e32 v231, 0xbfb8aa3b, v229
	v_exp_f32_e32 v230, v230
	v_exp_f32_e32 v231, v231
	v_mul_f32_e32 v232, v77, v121
	v_mul_f32_e32 v233, v69, v121
	v_add_f32_e32 v230, 1.0, v230
	v_add_f32_e32 v231, 1.0, v231
	v_rcp_f32_e32 v230, v230
	v_rcp_f32_e32 v231, v231
	v_mul_f32_e32 v228, v228, v230
	v_mul_f32_e32 v229, v229, v231
	v_mul_f32_e32 v232, v232, v228
	v_mul_f32_e32 v233, v233, v229
	v_cvt_pk_bf16_f32 v235, v232, v233
	global_store_dword v[174:175], v235, off
	v_lshl_add_u64 v[174:175], v[174:175], 0, s[98:99]
	v_lshl_add_u64 v[174:175], v[174:175], 0, s[44:45]
	v_mul_f32_e32 v228, v42, v98
	v_mul_f32_e32 v229, v34, v98
	v_mul_f32_e32 v230, 0xbfb8aa3b, v228
	v_mul_f32_e32 v231, 0xbfb8aa3b, v229
	v_exp_f32_e32 v230, v230
	v_exp_f32_e32 v231, v231
	v_mul_f32_e32 v232, v46, v98
	v_mul_f32_e32 v233, v38, v98
	v_add_f32_e32 v230, 1.0, v230
	v_add_f32_e32 v231, 1.0, v231
	v_rcp_f32_e32 v230, v230
	v_rcp_f32_e32 v231, v231
	v_mul_f32_e32 v228, v228, v230
	v_mul_f32_e32 v229, v229, v231
	v_mul_f32_e32 v232, v232, v228
	v_mul_f32_e32 v233, v233, v229
	v_cvt_pk_bf16_f32 v234, v232, v233
	global_store_dword v[174:175], v234, off
	v_lshl_add_u64 v[174:175], v[174:175], 0, s[98:99]
	s_and_b64 vcc, exec, s[10:11]
	s_cbranch_vccz .Lsw_pf_skip5
	s_mov_b32 m0, s27
	s_nop 0
	buffer_load_dwordx4 v248, s[36:39], s83 offen lds
.Lsw_pf_skip5:
	v_mul_f32_e32 v228, v43, v99
	v_mul_f32_e32 v229, v35, v99
	v_mul_f32_e32 v230, 0xbfb8aa3b, v228
	v_mul_f32_e32 v231, 0xbfb8aa3b, v229
	v_exp_f32_e32 v230, v230
	v_exp_f32_e32 v231, v231
	v_mul_f32_e32 v232, v47, v99
	v_mul_f32_e32 v233, v39, v99
	v_add_f32_e32 v230, 1.0, v230
	v_add_f32_e32 v231, 1.0, v231
	v_rcp_f32_e32 v230, v230
	v_rcp_f32_e32 v231, v231
	v_mul_f32_e32 v228, v228, v230
	v_mul_f32_e32 v229, v229, v231
	v_mul_f32_e32 v232, v232, v228
	v_mul_f32_e32 v233, v233, v229
	v_cvt_pk_bf16_f32 v235, v232, v233
	global_store_dword v[174:175], v235, off
	v_lshl_add_u64 v[174:175], v[174:175], 0, s[98:99]
	v_mul_f32_e32 v228, v44, v100
	v_mul_f32_e32 v229, v36, v100
	v_mul_f32_e32 v230, 0xbfb8aa3b, v228
	v_mul_f32_e32 v231, 0xbfb8aa3b, v229
	v_exp_f32_e32 v230, v230
	v_exp_f32_e32 v231, v231
	v_mul_f32_e32 v232, v48, v100
	v_mul_f32_e32 v233, v40, v100
	v_add_f32_e32 v230, 1.0, v230
	v_add_f32_e32 v231, 1.0, v231
	v_rcp_f32_e32 v230, v230
	v_rcp_f32_e32 v231, v231
	v_mul_f32_e32 v228, v228, v230
	v_mul_f32_e32 v229, v229, v231
	v_mul_f32_e32 v232, v232, v228
	v_mul_f32_e32 v233, v233, v229
	v_cvt_pk_bf16_f32 v234, v232, v233
	global_store_dword v[174:175], v234, off
	v_lshl_add_u64 v[174:175], v[174:175], 0, s[98:99]
	v_mul_f32_e32 v228, v45, v101
	v_mul_f32_e32 v229, v37, v101
	v_mul_f32_e32 v230, 0xbfb8aa3b, v228
	v_mul_f32_e32 v231, 0xbfb8aa3b, v229
	v_exp_f32_e32 v230, v230
	v_exp_f32_e32 v231, v231
	v_mul_f32_e32 v232, v49, v101
	v_mul_f32_e32 v233, v41, v101
	v_add_f32_e32 v230, 1.0, v230
	v_add_f32_e32 v231, 1.0, v231
	v_rcp_f32_e32 v230, v230
	v_rcp_f32_e32 v231, v231
	v_mul_f32_e32 v228, v228, v230
	v_mul_f32_e32 v229, v229, v231
	v_mul_f32_e32 v232, v232, v228
	v_mul_f32_e32 v233, v233, v229
	v_cvt_pk_bf16_f32 v235, v232, v233
	global_store_dword v[174:175], v235, off
	v_lshl_add_u64 v[174:175], v[174:175], 0, s[98:99]
	v_lshl_add_u64 v[174:175], v[174:175], 0, s[44:45]
	v_mul_f32_e32 v228, v26, v78
	v_mul_f32_e32 v229, v18, v78
	v_mul_f32_e32 v230, 0xbfb8aa3b, v228
	v_mul_f32_e32 v231, 0xbfb8aa3b, v229
	v_exp_f32_e32 v230, v230
	v_exp_f32_e32 v231, v231
	v_mul_f32_e32 v232, v30, v78
	v_mul_f32_e32 v233, v22, v78
	v_add_f32_e32 v230, 1.0, v230
	v_add_f32_e32 v231, 1.0, v231
	v_rcp_f32_e32 v230, v230
	v_rcp_f32_e32 v231, v231
	v_mul_f32_e32 v228, v228, v230
	v_mul_f32_e32 v229, v229, v231
	v_mul_f32_e32 v232, v232, v228
	v_mul_f32_e32 v233, v233, v229
	v_cvt_pk_bf16_f32 v234, v232, v233
	global_store_dword v[174:175], v234, off
	v_lshl_add_u64 v[174:175], v[174:175], 0, s[98:99]
	s_and_b64 vcc, exec, s[10:11]
	s_cbranch_vccz .Lsw_pf_skip6
	s_mov_b32 m0, s28
	s_nop 0
	buffer_load_dwordx4 v201, s[64:67], s90 offen lds
.Lsw_pf_skip6:
	v_mul_f32_e32 v228, v27, v79
	v_mul_f32_e32 v229, v19, v79
	v_mul_f32_e32 v230, 0xbfb8aa3b, v228
	v_mul_f32_e32 v231, 0xbfb8aa3b, v229
	v_exp_f32_e32 v230, v230
	v_exp_f32_e32 v231, v231
	v_mul_f32_e32 v232, v31, v79
	v_mul_f32_e32 v233, v23, v79
	v_add_f32_e32 v230, 1.0, v230
	v_add_f32_e32 v231, 1.0, v231
	v_rcp_f32_e32 v230, v230
	v_rcp_f32_e32 v231, v231
	v_mul_f32_e32 v228, v228, v230
	v_mul_f32_e32 v229, v229, v231
	v_mul_f32_e32 v232, v232, v228
	v_mul_f32_e32 v233, v233, v229
	v_cvt_pk_bf16_f32 v235, v232, v233
	global_store_dword v[174:175], v235, off
	v_lshl_add_u64 v[174:175], v[174:175], 0, s[98:99]
	v_mul_f32_e32 v228, v28, v80
	v_mul_f32_e32 v229, v20, v80
	v_mul_f32_e32 v230, 0xbfb8aa3b, v228
	v_mul_f32_e32 v231, 0xbfb8aa3b, v229
	v_exp_f32_e32 v230, v230
	v_exp_f32_e32 v231, v231
	v_mul_f32_e32 v232, v32, v80
	v_mul_f32_e32 v233, v24, v80
	v_add_f32_e32 v230, 1.0, v230
	v_add_f32_e32 v231, 1.0, v231
	v_rcp_f32_e32 v230, v230
	v_rcp_f32_e32 v231, v231
	v_mul_f32_e32 v228, v228, v230
	v_mul_f32_e32 v229, v229, v231
	v_mul_f32_e32 v232, v232, v228
	v_mul_f32_e32 v233, v233, v229
	v_cvt_pk_bf16_f32 v234, v232, v233
	global_store_dword v[174:175], v234, off
	v_lshl_add_u64 v[174:175], v[174:175], 0, s[98:99]
	v_mul_f32_e32 v228, v29, v81
	v_mul_f32_e32 v229, v21, v81
	v_mul_f32_e32 v230, 0xbfb8aa3b, v228
	v_mul_f32_e32 v231, 0xbfb8aa3b, v229
	v_exp_f32_e32 v230, v230
	v_exp_f32_e32 v231, v231
	v_mul_f32_e32 v232, v33, v81
	v_mul_f32_e32 v233, v25, v81
	v_add_f32_e32 v230, 1.0, v230
	v_add_f32_e32 v231, 1.0, v231
	v_rcp_f32_e32 v230, v230
	v_rcp_f32_e32 v231, v231
	v_mul_f32_e32 v228, v228, v230
	v_mul_f32_e32 v229, v229, v231
	v_mul_f32_e32 v232, v232, v228
	v_mul_f32_e32 v233, v233, v229
	v_cvt_pk_bf16_f32 v235, v232, v233
	global_store_dword v[174:175], v235, off
	v_lshl_add_u64 v[174:175], v[174:175], 0, s[98:99]
	v_lshl_add_u64 v[174:175], v[174:175], 0, s[44:45]
	v_mul_f32_e32 v228, v10, v58
	v_mul_f32_e32 v229, v2, v58
	v_mul_f32_e32 v230, 0xbfb8aa3b, v228
	v_mul_f32_e32 v231, 0xbfb8aa3b, v229
	v_exp_f32_e32 v230, v230
	v_exp_f32_e32 v231, v231
	v_mul_f32_e32 v232, v14, v58
	v_mul_f32_e32 v233, v6, v58
	v_add_f32_e32 v230, 1.0, v230
	v_add_f32_e32 v231, 1.0, v231
	v_rcp_f32_e32 v230, v230
	v_rcp_f32_e32 v231, v231
	v_mul_f32_e32 v228, v228, v230
	v_mul_f32_e32 v229, v229, v231
	v_mul_f32_e32 v232, v232, v228
	v_mul_f32_e32 v233, v233, v229
	v_cvt_pk_bf16_f32 v234, v232, v233
	global_store_dword v[174:175], v234, off
	v_lshl_add_u64 v[174:175], v[174:175], 0, s[98:99]
	s_and_b64 vcc, exec, s[10:11]
	s_cbranch_vccz .Lsw_pf_skip7
	s_mov_b32 m0, s29
	s_nop 0
	buffer_load_dwordx4 v248, s[36:39], s90 offen lds
.Lsw_pf_skip7:
	v_mul_f32_e32 v228, v11, v59
	v_mul_f32_e32 v229, v3, v59
	v_mul_f32_e32 v230, 0xbfb8aa3b, v228
	v_mul_f32_e32 v231, 0xbfb8aa3b, v229
	v_exp_f32_e32 v230, v230
	v_exp_f32_e32 v231, v231
	v_mul_f32_e32 v232, v15, v59
	v_mul_f32_e32 v233, v7, v59
	v_add_f32_e32 v230, 1.0, v230
	v_add_f32_e32 v231, 1.0, v231
	v_rcp_f32_e32 v230, v230
	v_rcp_f32_e32 v231, v231
	v_mul_f32_e32 v228, v228, v230
	v_mul_f32_e32 v229, v229, v231
	v_mul_f32_e32 v232, v232, v228
	v_mul_f32_e32 v233, v233, v229
	v_cvt_pk_bf16_f32 v235, v232, v233
	global_store_dword v[174:175], v235, off
	v_lshl_add_u64 v[174:175], v[174:175], 0, s[98:99]
	v_mul_f32_e32 v228, v12, v60
	v_mul_f32_e32 v229, v4, v60
	v_mul_f32_e32 v230, 0xbfb8aa3b, v228
	v_mul_f32_e32 v231, 0xbfb8aa3b, v229
	v_exp_f32_e32 v230, v230
	v_exp_f32_e32 v231, v231
	v_mul_f32_e32 v232, v16, v60
	v_mul_f32_e32 v233, v8, v60
	v_add_f32_e32 v230, 1.0, v230
	v_add_f32_e32 v231, 1.0, v231
	v_rcp_f32_e32 v230, v230
	v_rcp_f32_e32 v231, v231
	v_mul_f32_e32 v228, v228, v230
	v_mul_f32_e32 v229, v229, v231
	v_mul_f32_e32 v232, v232, v228
	v_mul_f32_e32 v233, v233, v229
	v_cvt_pk_bf16_f32 v234, v232, v233
	global_store_dword v[174:175], v234, off
	v_lshl_add_u64 v[174:175], v[174:175], 0, s[98:99]
	v_mul_f32_e32 v228, v13, v61
	v_mul_f32_e32 v229, v5, v61
	v_mul_f32_e32 v230, 0xbfb8aa3b, v228
	v_mul_f32_e32 v231, 0xbfb8aa3b, v229
	v_exp_f32_e32 v230, v230
	v_exp_f32_e32 v231, v231
	v_mul_f32_e32 v232, v17, v61
	v_mul_f32_e32 v233, v9, v61
	v_add_f32_e32 v230, 1.0, v230
	v_add_f32_e32 v231, 1.0, v231
	v_rcp_f32_e32 v230, v230
	v_rcp_f32_e32 v231, v231
	v_mul_f32_e32 v228, v228, v230
	v_mul_f32_e32 v229, v229, v231
	v_mul_f32_e32 v232, v232, v228
	v_mul_f32_e32 v233, v233, v229
	v_cvt_pk_bf16_f32 v235, v232, v233
	global_store_dword v[174:175], v235, off
	v_lshl_add_u64 v[174:175], v[174:175], 0, s[98:99]
	v_lshl_add_u64 v[174:175], v[174:175], 0, s[44:45]
